# v35 (4 LDS buffer sets in diff loop, WAR barriers removed, prio) + back-edge rotation in diff and MLA loops
# speedup vs baseline: 1.0099x; 1.0059x over previous
; #define SBAR() __builtin_amdgcn_sched_barrier(0)
; #define SLOAD(k0) do { vs0 = *(const bf16x8*)(vp0 + (long)(k0) * ldv); vs1 = *(const bf16x8*)(vp0 + (long)((k0) + 32) * ldv); \
;     ksg[0] = *(const bf16x8*)(kp0 + (long)(k0) * ldk0); \
;     if constexpr (DQK == 192) { ksg[1] = *(const bf16x8*)(kp0 + (long)((k0) + 32) * ldk0); ksg[2] = *(const bf16x8*)(kp2 + (long)(k0) * ldk1); } } while (0)
; #define SWAIT() asm volatile("s_waitcnt vmcnt(0)" ::: "memory")
; DEVI void partialSM(f32x16& p0, f32x16& p1, float& m_reg, float& mn, float& alpha, float scale) {
;   const float C = scale * 1.4426950408889634f;
;   float pmax = p0[0];
; #pragma unroll
;   for (int r = 1; r < 16; ++r) pmax = fmaxf(pmax, p0[r]);
; #pragma unroll
;   for (int r = 0; r < 16; ++r) pmax = fmaxf(pmax, p1[r]);
;   { auto rr = __builtin_amdgcn_permlane32_swap(__float_as_uint(pmax), __float_as_uint(pmax), false, false);
;     pmax = fmaxf(__uint_as_float(rr[0]), __uint_as_float(rr[1])); }
;   if (__builtin_expect(__all(pmax - m_reg <= ATT_THR / scale), 1)) { mn = m_reg; alpha = 1.f; }
;   else { mn = fmaxf(m_reg, pmax); alpha = __builtin_amdgcn_exp2f((m_reg - mn) * C); m_reg = mn; }
;   const float mnC = -mn * C;
; #pragma unroll
;   for (int r = 0; r < 16; ++r) p0[r] = fmaf(p0[r], C, mnC);
; #pragma unroll
;   for (int r = 0; r < 16; ++r) p1[r] = fmaf(p1[r], C, mnC);
; #pragma unroll
;   for (int r = 0; r < 16; ++r) p0[r] = __builtin_amdgcn_exp2f(p0[r]);
; }
; template <int DQK, bool PIPE>
; DEVI void attn_body(const u16* __restrict__ Qb, int ldq, const u16* __restrict__ K0, int ldk0, const u16* __restrict__ K1, int ldk1,
;                     const u16* __restrict__ Vh, int ldv, u16* __restrict__ Ob, int ldo, int seq, float scale, char* lds) {
;     ...
;       __syncthreads(); SWAIT(); SWRITE(0);
;       RESC(alB); __syncthreads();
;       SBAR(); QKT(pA0, pA1, K_lds);
;       finishSM(pB0, pB1, alB, l_reg, pa0, pa1, pa2, pa3); SBAR();
;       SLOAD((j + 2) * 64); SBAR();
;       pv_d0(o, vb0 + SHM_V, pa0, pa1, pa2, pa3); partialSM(pA0, pA1, m_reg, mnA, alA, scale);
;       __syncthreads(); SWAIT(); SWRITE(1);
;       RESC(alA); __syncthreads();
;     }
.LBB0_477:
	v_cndmask_b32_e64 v148, v130, v148, s[8:9]
	v_mul_f32_e32 v112, 0xbe38aa3b, v148
	v_mov_b32_e32 v113, v112
	v_fmamk_f32 v80, v80, 0x3e38aa3b, v112
	v_fmamk_f32 v81, v81, 0x3e38aa3b, v112
	v_fmamk_f32 v82, v82, 0x3e38aa3b, v112
	v_fmamk_f32 v83, v83, 0x3e38aa3b, v112
	v_fmamk_f32 v84, v84, 0x3e38aa3b, v112
	v_fmamk_f32 v85, v85, 0x3e38aa3b, v112
	v_fmamk_f32 v86, v86, 0x3e38aa3b, v112
	v_fmamk_f32 v87, v87, 0x3e38aa3b, v112
	v_fmamk_f32 v88, v88, 0x3e38aa3b, v112
	v_fmamk_f32 v89, v89, 0x3e38aa3b, v112
	v_fmamk_f32 v90, v90, 0x3e38aa3b, v112
	v_fmamk_f32 v91, v91, 0x3e38aa3b, v112
	v_fmamk_f32 v92, v92, 0x3e38aa3b, v112
	v_fmamk_f32 v93, v93, 0x3e38aa3b, v112
	v_fmamk_f32 v94, v94, 0x3e38aa3b, v112
	v_fmac_f32_e32 v113, 0x3e38aa3b, v95
	v_exp_f32_e32 v157, v80
	v_exp_f32_e32 v159, v81
	v_exp_f32_e32 v161, v82
	v_exp_f32_e32 v163, v83
	v_exp_f32_e32 v165, v84
	v_exp_f32_e32 v167, v85
	v_exp_f32_e32 v168, v86
	v_exp_f32_e32 v170, v87
	v_exp_f32_e32 v155, v88
	v_exp_f32_e32 v156, v89
	v_exp_f32_e32 v158, v90
	v_exp_f32_e32 v160, v91
	v_exp_f32_e32 v162, v92
	v_exp_f32_e32 v164, v93
	v_exp_f32_e32 v166, v94
	v_exp_f32_e32 v169, v113
	v_pk_fma_f32 v[132:133], v[64:65], s[20:21], v[112:113] op_sel_hi:[1,0,0]
	v_add_f32_e32 v64, v149, v150
	v_fmac_f32_e32 v64, v147, v137
	v_add_f32_e32 v137, v153, v154
	s_add_i32 s15, s15, 2
	v_pk_fma_f32 v[130:131], v[66:67], s[20:21], v[112:113] op_sel_hi:[1,0,0]
	v_pk_fma_f32 v[120:121], v[68:69], s[20:21], v[112:113] op_sel_hi:[1,0,0]
	v_pk_fma_f32 v[116:117], v[70:71], s[20:21], v[112:113] op_sel_hi:[1,0,0]
	v_pk_fma_f32 v[114:115], v[72:73], s[20:21], v[112:113] op_sel_hi:[1,0,0]
	v_pk_fma_f32 v[122:123], v[74:75], s[20:21], v[112:113] op_sel_hi:[1,0,0]
	v_pk_fma_f32 v[118:119], v[76:77], s[20:21], v[112:113] op_sel_hi:[1,0,0]
	v_pk_fma_f32 v[112:113], v[78:79], s[20:21], v[112:113] op_sel_hi:[1,0,0]
	v_fmac_f32_e32 v137, v64, v152
	v_lshl_add_u64 v[126:127], v[126:127], 0, s[22:23]
	s_cmpk_gt_u32 s15, 0x80
	v_lshl_add_u64 v[128:129], v[128:129], 0, s[22:23]
	v_xor_b32_e32 v138, 0x10000, v138
	v_xor_b32_e32 v139, 0x10000, v139
	v_xor_b32_e32 v140, 0x10000, v140
	v_xor_b32_e32 v141, 0x10000, v141
	v_xor_b32_e32 v142, 0x10000, v142
	v_mov_b32_e32 v147, v151
	s_waitcnt lgkmcnt(0)
	s_barrier
	s_cbranch_scc0 .LBB0_469
